# aligned combo12 + background conversion share of the barrier after PL (layer 0) moved into the barrier after UP, done by the workgroups that idle there
# baseline (speedup 1.0000x reference)
; #define LAS __attribute__((address_space(3)))
; __device__ __forceinline__ void cv_background(Frame& F, const CvPtrs& P, int s) {
;     int tv = threadIdx.x; asm volatile("" : "+v"(tv));
;     const int w = __builtin_amdgcn_readfirstlane(tv >> 6) - 1, lane = tv & 63, nbw = F.G * (NWAVES - 1);
;     LAS float* scr = (LAS float*)(F.lds + RING_OFF + (w + 1) * 16384);
;     const int sh_ = cv_bg_share(s), hi = (sh_ + 1) * CV_BG_PER < CV_BG_TOTAL ? (sh_ + 1) * CV_BG_PER : CV_BG_TOTAL;
;     for (int j = sh_ * CV_BG_PER + F.vcu * (NWAVES - 1) + w; j < hi; j += nbw) {
;         if (j < BG_L0A) cv_dispatch(P, F.ws, F.out, 0, CV_BG0 + j, scr, lane);
;         else if (j < BG_L0A + BG_P_ITEMS) cv_p_item(F.ws, P.p + (size_t)M * PLE, j - BG_L0A, lane);
;         else if (j < BG_L1_AT) cv_dispatch(P, F.ws, F.out, 0, CV_BG0 + j - BG_P_ITEMS, scr, lane);
;         else { const int jj = j - BG_L1_AT; cv_dispatch(P, F.ws, F.out, 1, jj < CI_IN ? jj : (jj < CI_IN + CI_PL ? CV_NITEMS - CI_PL + (jj - CI_IN) : jj - CI_PL), scr, lane); }
;     }
; }
.LBB0_801:
	s_add_i32 s1, s9, 0x6d6
	s_ashr_i32 s0, s8, 6
	s_min_u32 s6, s1, 0x3880
	s_mov_b32 s98, s34
	s_mov_b32 s99, s87
	s_cmpk_lg_u32 s87, 0x100
	s_cbranch_scc1 .Lbg_idx_done
	s_and_b32 s4, s34, 31
	s_lshr_b32 s5, s34, 5
	s_cmp_eq_u32 s90, 7
	s_cbranch_scc1 .LBB0_1015
	s_cmp_eq_u32 s90, 5
	s_cbranch_scc1 .Lbg_up
	s_cmp_eq_u32 s90, 1
	s_cbranch_scc1 .Lbg_in
	s_cmp_eq_u32 s90, 8
	s_cbranch_scc0 .Lbg_idx_done

; #define LAS __attribute__((address_space(3)))
; __device__ __forceinline__ void cv_background(Frame& F, const CvPtrs& P, int s) {
;     int tv = threadIdx.x; asm volatile("" : "+v"(tv));
;     const int w = __builtin_amdgcn_readfirstlane(tv >> 6) - 1, lane = tv & 63, nbw = F.G * (NWAVES - 1);
;     LAS float* scr = (LAS float*)(F.lds + RING_OFF + (w + 1) * 16384);
;     const int sh_ = cv_bg_share(s), hi = (sh_ + 1) * CV_BG_PER < CV_BG_TOTAL ? (sh_ + 1) * CV_BG_PER : CV_BG_TOTAL;
;     for (int j = sh_ * CV_BG_PER + F.vcu * (NWAVES - 1) + w; j < hi; j += nbw) {
.Lbg_up:
	s_lshl_b32 s4, s4, 3
	s_add_u32 s4, s4, s5
	s_cmpk_lt_u32 s4, 0xc2
	s_cbranch_scc1 .LBB0_1015
	s_sub_u32 s98, s4, 0xc2
	s_movk_i32 s99, 0x3e
	s_add_i32 s6, s9, 0xdac
	s_min_u32 s6, s6, 0x3880
